# t8 + ffn_w_in conversion items taken kb-fastest (neighbouring waves write adjacent 128-B pieces of the same bf16 rows)
# baseline (speedup 1.0000x reference)
.LBB0_235:
	s_andn2_b64 vcc, exec, s[6:7]
	s_cbranch_vccnz .LBB0_238
	s_and_b32 s6, s14, 31
	s_lshr_b32 s7, s14, 5
	s_mul_i32 s15, s15, 0x5600000
	s_add_u32 s12, s64, s15
	s_addc_u32 s13, s65, 0
	s_lshl_b32 s8, s6, 6
	s_lshl_b32 s40, s7, 7
	s_add_u32 s10, s24, s4
	s_addc_u32 s11, s25, 0
	s_lshl_b32 s4, s7, 8
	s_add_i32 s14, s4, 0xffffd580
	s_cmp_lt_i32 s7, 43
	s_cselect_b64 vcc, -1, 0
	s_and_b64 s[6:7], vcc, exec
	v_cndmask_b32_e32 v134, v171, v172, vcc
	s_cselect_b32 s4, s4, s14
	s_mov_b64 s[6:7], 0x800
	s_movk_i32 s39, 0x2b00
	s_branch .LBB0_239

.LBB0_305:
	s_andn2_b64 vcc, exec, s[6:7]
	s_cbranch_vccnz .LBB0_308
	s_and_b32 s6, s16, 31
	s_lshr_b32 s7, s16, 5
	s_mul_i32 s17, s17, 0x5600000
	s_add_u32 s14, s64, s17
	s_addc_u32 s15, s65, 0
	s_lshl_b32 s10, s6, 6
	s_lshl_b32 s40, s7, 7
	s_add_u32 s12, s26, s4
	s_addc_u32 s13, s27, 0
	s_lshl_b32 s4, s7, 8
	s_add_i32 s16, s4, 0xffffd580
	s_cmp_lt_i32 s7, 43
	s_cselect_b64 vcc, -1, 0
	s_and_b64 s[6:7], vcc, exec
	v_cndmask_b32_e32 v132, v168, v169, vcc
	s_cselect_b32 s4, s4, s16
	s_mov_b64 s[6:7], 0x800
	s_movk_i32 s39, 0x2b00
	s_branch .LBB0_309

.LBB0_535:
	s_andn2_b64 vcc, exec, s[4:5]
	s_cbranch_vccnz .LBB0_538
	s_and_b32 s4, s13, 31
	s_lshr_b32 s5, s13, 5
	s_mul_i32 s16, s16, 0x5600000
	v_readlane_b32 s64, v252, 19
	v_readlane_b32 s65, v252, 20
	s_add_u32 s10, s64, s16
	s_addc_u32 s11, s65, 0
	s_lshl_b32 s6, s4, 6
	s_lshl_b32 s23, s5, 7
	v_readlane_b32 s4, v252, 53
	s_add_u32 s8, s4, s12
	v_readlane_b32 s4, v252, 54
	s_addc_u32 s9, s4, 0
	s_lshl_b32 s12, s5, 8
	s_add_i32 s13, s12, 0xffffd580
	s_cmp_lt_i32 s5, 43
	s_cselect_b64 vcc, -1, 0
	v_mov_b32_e32 v2, 0xbf317218
	v_mov_b32_e32 v3, 0xbfb8aa3b
	s_and_b64 s[4:5], vcc, exec
	v_cndmask_b32_e32 v132, v2, v3, vcc
	s_cselect_b32 s20, s12, s13
	s_mov_b64 s[4:5], 0x800
	s_movk_i32 s21, 0x2b00
	v_readlane_b32 s66, v252, 21
	v_readlane_b32 s67, v252, 22
	v_readlane_b32 s68, v252, 23
	v_readlane_b32 s69, v252, 24
	v_readlane_b32 s70, v252, 25
	v_readlane_b32 s71, v252, 26
	v_readlane_b32 s72, v252, 27
	v_readlane_b32 s73, v252, 28
	v_readlane_b32 s74, v252, 29
	v_readlane_b32 s75, v252, 30
	v_readlane_b32 s76, v252, 31
	v_readlane_b32 s77, v252, 32
	v_readlane_b32 s78, v252, 33
	v_readlane_b32 s79, v252, 34
	s_branch .LBB0_539
